# phase 0 modulation item: the 12 serialized silu(cond) loads per thread issued up front with counted waits
# speedup vs baseline: 1.0016x; 1.0016x over previous
.LBB0_707:
	s_and_b64 vcc, exec, s[0:1]
	s_cbranch_vccz .LBB0_683
	v_mov_b32 v0, 0
	s_movk_i32 s0, 0xbff
	v_add_u32_sdwa v72, v0, v160 dst_sel:DWORD dst_unused:UNUSED_PAD src0_sel:DWORD src1_sel:BYTE_0
	v_cmp_lt_i32_e32 vcc, s0, v72
	v_lshlrev_b32_e32 v2, 2, v72
	s_and_saveexec_b64 s[0:1], vcc
	s_xor_b64 s[0:1], exec, s[0:1]
	v_lshlrev_b32_e32 v2, 2, v72
	s_andn2_saveexec_b64 s[0:1], s[0:1]
	s_cbranch_execz .LBB0_718
	v_add_u32_e32 v3, s15, v2
	v_readlane_b32 s60, v253, 20
	v_readlane_b32 s61, v253, 21
	v_readlane_b32 s62, v253, 22
	v_readlane_b32 s63, v253, 23
	v_readlane_b32 s64, v253, 24
	v_readlane_b32 s65, v253, 25
	v_readlane_b32 s66, v253, 26
	v_readlane_b32 s67, v253, 27
	v_readlane_b32 s68, v253, 28
	v_readlane_b32 s69, v253, 29
	v_readlane_b32 s70, v253, 30
	v_readlane_b32 s71, v253, 31
	v_readlane_b32 s72, v253, 32
	v_readlane_b32 s73, v253, 33
	v_readlane_b32 s74, v253, 34
	v_readlane_b32 s75, v253, 35
	v_add_u32_e32 v16, 0x1000, v2
	s_nop 3
	global_load_dword v4, v2, s[74:75]
	global_load_dword v5, v2, s[74:75] offset:1024
	global_load_dword v6, v2, s[74:75] offset:2048
	global_load_dword v7, v2, s[74:75] offset:3072
	global_load_dword v8, v2, s[72:73]
	global_load_dword v9, v2, s[72:73] offset:1024
	global_load_dword v10, v2, s[72:73] offset:2048
	global_load_dword v11, v2, s[72:73] offset:3072
	global_load_dword v12, v16, s[72:73]
	global_load_dword v13, v16, s[72:73] offset:1024
	global_load_dword v14, v16, s[72:73] offset:2048
	global_load_dword v15, v16, s[72:73] offset:3072
	s_waitcnt vmcnt(11)
	v_mul_f32_e32 v1, 0xbfb8aa3b, v4
	v_exp_f32_e32 v1, v1
	s_nop 0
	v_add_f32_e32 v1, 1.0, v1
	v_rcp_f32_e32 v1, v1
	s_nop 0
	v_mul_f32_e32 v0, v4, v1
	ds_write_b32 v3, v0
	s_waitcnt vmcnt(10)
	v_mul_f32_e32 v1, 0xbfb8aa3b, v5
	v_exp_f32_e32 v1, v1
	s_nop 0
	v_add_f32_e32 v1, 1.0, v1
	v_rcp_f32_e32 v1, v1
	s_nop 0
	v_mul_f32_e32 v0, v5, v1
	ds_write_b32 v3, v0 offset:1024
	s_waitcnt vmcnt(9)
	v_mul_f32_e32 v1, 0xbfb8aa3b, v6
	v_exp_f32_e32 v1, v1
	s_nop 0
	v_add_f32_e32 v1, 1.0, v1
	v_rcp_f32_e32 v1, v1
	s_nop 0
	v_mul_f32_e32 v0, v6, v1
	ds_write_b32 v3, v0 offset:2048
	s_waitcnt vmcnt(8)
	v_mul_f32_e32 v1, 0xbfb8aa3b, v7
	v_exp_f32_e32 v1, v1
	s_nop 0
	v_add_f32_e32 v1, 1.0, v1
	v_rcp_f32_e32 v1, v1
	s_nop 0
	v_mul_f32_e32 v0, v7, v1
	ds_write_b32 v3, v0 offset:3072
	s_waitcnt vmcnt(7)
	v_mul_f32_e32 v1, 0xbfb8aa3b, v8
	v_exp_f32_e32 v1, v1
	s_nop 0
	v_add_f32_e32 v1, 1.0, v1
	v_rcp_f32_e32 v1, v1
	s_nop 0
	v_mul_f32_e32 v0, v8, v1
	ds_write_b32 v3, v0 offset:4096
	s_waitcnt vmcnt(6)
	v_mul_f32_e32 v1, 0xbfb8aa3b, v9
	v_exp_f32_e32 v1, v1
	s_nop 0
	v_add_f32_e32 v1, 1.0, v1
	v_rcp_f32_e32 v1, v1
	s_nop 0
	v_mul_f32_e32 v0, v9, v1
	ds_write_b32 v3, v0 offset:5120
	s_waitcnt vmcnt(5)
	v_mul_f32_e32 v1, 0xbfb8aa3b, v10
	v_exp_f32_e32 v1, v1
	s_nop 0
	v_add_f32_e32 v1, 1.0, v1
	v_rcp_f32_e32 v1, v1
	s_nop 0
	v_mul_f32_e32 v0, v10, v1
	ds_write_b32 v3, v0 offset:6144
	s_waitcnt vmcnt(4)
	v_mul_f32_e32 v1, 0xbfb8aa3b, v11
	v_exp_f32_e32 v1, v1
	s_nop 0
	v_add_f32_e32 v1, 1.0, v1
	v_rcp_f32_e32 v1, v1
	s_nop 0
	v_mul_f32_e32 v0, v11, v1
	ds_write_b32 v3, v0 offset:7168
	s_waitcnt vmcnt(3)
	v_mul_f32_e32 v1, 0xbfb8aa3b, v12
	v_exp_f32_e32 v1, v1
	s_nop 0
	v_add_f32_e32 v1, 1.0, v1
	v_rcp_f32_e32 v1, v1
	s_nop 0
	v_mul_f32_e32 v0, v12, v1
	ds_write_b32 v3, v0 offset:8192
	s_waitcnt vmcnt(2)
	v_mul_f32_e32 v1, 0xbfb8aa3b, v13
	v_exp_f32_e32 v1, v1
	s_nop 0
	v_add_f32_e32 v1, 1.0, v1
	v_rcp_f32_e32 v1, v1
	s_nop 0
	v_mul_f32_e32 v0, v13, v1
	ds_write_b32 v3, v0 offset:9216
	s_waitcnt vmcnt(1)
	v_mul_f32_e32 v1, 0xbfb8aa3b, v14
	v_exp_f32_e32 v1, v1
	s_nop 0
	v_add_f32_e32 v1, 1.0, v1
	v_rcp_f32_e32 v1, v1
	s_nop 0
	v_mul_f32_e32 v0, v14, v1
	ds_write_b32 v3, v0 offset:10240
	s_waitcnt vmcnt(0)
	v_mul_f32_e32 v1, 0xbfb8aa3b, v15
	v_exp_f32_e32 v1, v1
	s_nop 0
	v_add_f32_e32 v1, 1.0, v1
	v_rcp_f32_e32 v1, v1
	s_nop 0
	v_mul_f32_e32 v0, v15, v1
	ds_write_b32 v3, v0 offset:11264
